# SSD prompt chain: one static s_setprio 1 for waves 4-7 (the second wave on each SIMD) for the length of the 17-chunk loop
# speedup vs baseline: 1.0055x; 1.0055x over previous
; __device__ __forceinline__ void ssd_prompt(const Params& p, LAS unsigned char* lds, int b, int h) {
;     ...
;     const int trow = 16 * wid + fr;
;     u32x4 rx[2], rb[4], rc[4]; u32x2 rz[4]; float rd0 = 0.f, rd1 = 0.f, ra0 = 0.f, ra1 = 0.f;
;     ...
;     SSD_ISSUE(0); SSD_ISSUE_Z(0);
;     for (int c = 0; c < 17; ++c) {
;         const int base = b * TP + c * 128;
;         if (wid == 0) { const int t0 = 2 * lane; sDt[t0] = rd0; sDt[t0 + 1] = rd1; sAc[t0] = ra0; sAc[t0 + 1] = ra1; }
; #pragma unroll
;         for (int i = 0; i < 2; ++i) { const int v_ = tid + 512 * i; *(LAS u32x4*)(sX + (v_ >> 3) * XROW + (v_ & 7) * 8) = rx[i]; }
; #pragma unroll
;         for (int i = 0; i < 4; ++i) { const int v_ = tid + 512 * i; *(LAS u32x4*)(sB + (v_ >> 4) * LROW + (v_ & 15) * 8) = rb[i]; *(LAS u32x4*)(sC + (v_ >> 4) * LROW + (v_ & 15) * 8) = rc[i]; }
;         __syncthreads();
;         const int cn = c < 16 ? c + 1 : 16;
;         SSD_ISSUE(cn);
;         if (tid < 128) sW[tid] = __expf(sAc[127] - sAc[tid]) * sDt[tid];
;         const float act = sAc[trow];
;         bf16x8 cf[4];
; #pragma unroll
;         for (int kk = 0; kk < 4; ++kk) cf[kk] = *(const LAS bf16x8*)(sC + trow * LROW + 32 * kk + 8 * fq);
;         f32x4 d[8];
; #pragma unroll
;         for (int st = 0; st < 8; ++st) d[st] = (f32x4){0.f, 0.f, 0.f, 0.f};
; #pragma unroll
;         for (int kk = 0; kk < 4; ++kk) {
;             bf16x8 bfr[8];
; #pragma unroll
;             for (int st = 0; st < 8; ++st) bfr[st] = *(const LAS bf16x8*)(sB + (16 * st + fr) * LROW + 32 * kk + 8 * fq);
; #pragma unroll
;             for (int st = 0; st < 8; ++st) d[st] = __builtin_amdgcn_mfma_f32_16x16x32_bf16(bfr[st], cf[kk], d[st], 0, 0, 0);
;         }
;         bf16x8 gfrag[4];
;         {
; #pragma unroll
;             for (int kb = 0; kb < 4; ++kb) {
;                 f32x4 acs[2], dts[2];
; #pragma unroll
;                 for (int hf = 0; hf < 2; ++hf) { acs[hf] = *(const LAS f32x4*)(sAc + 16 * (2 * kb + hf) + 4 * fq); dts[hf] = *(const LAS f32x4*)(sDt + 16 * (2 * kb + hf) + 4 * fq); }
;                 unsigned pkd[4];
; #pragma unroll
;                 for (int hf = 0; hf < 2; ++hf) { const int st = 2 * kb + hf; float gv[4];
; #pragma unroll
;                     for (int jj = 0; jj < 4; ++jj) { const int s = 16 * st + 4 * fq + jj; gv[jj] = (s <= trow) ? d[st][jj] * __expf(act - acs[hf][jj]) * dts[hf][jj] : 0.f; }
.LBB0_528:
	s_ashr_i32 s3, s3, 6
	v_and_b32_e32 v150, 15, v40
	s_lshl_b32 s70, s3, 4
	v_or_b32_e32 v126, s70, v150
	v_ashrrev_i32_e32 v127, 31, v126
	v_lshl_add_u64 v[46:47], s[6:7], 0, v[126:127]
	s_movk_i32 s83, 0x6a00
	v_mov_b64_e32 v[48:49], s[92:93]
	v_mad_u64_u32 v[48:49], s[12:13], v46, s83, v[48:49]
	v_mov_b32_e32 v46, v49
	v_mad_u64_u32 v[46:47], s[12:13], v47, s83, v[46:47]
	v_lshrrev_b32_e32 v45, 4, v44
	v_mov_b32_e32 v49, v46
	s_lshl_b32 s94, s0, 1
	v_lshl_add_u64 v[46:47], v[48:49], 0, s[94:95]
	v_lshlrev_b32_e32 v48, 3, v45
	v_mov_b32_e32 v49, v109
	v_lshl_add_u64 v[46:47], v[46:47], 0, v[48:49]
	global_load_dwordx2 v[148:149], v[46:47], off
	global_load_dwordx2 v[146:147], v[46:47], off offset:32
	global_load_dwordx2 v[144:145], v[46:47], off offset:64
	global_load_dwordx2 v[140:141], v[46:47], off offset:96
	s_movk_i32 s0, 0x80
	v_cmp_gt_i32_e64 s[0:1], s0, v40
	s_add_i32 s11, 0, 0x19e00
	s_add_i32 s12, 0, 0x19c00
	v_writelane_b32 v244, s0, 61
	v_lshlrev_b32_e32 v53, 2, v151
	s_movk_i32 s71, 0x110
	v_writelane_b32 v244, s1, 62
	s_add_u32 s0, s88, s10
	s_addc_u32 s1, s89, 0
	s_add_u32 s18, s0, 0x1bdf0000
	s_addc_u32 s19, s1, 0
	s_add_u32 s0, s92, s94
	v_and_b32_e32 v52, 48, v44
	s_addc_u32 s1, s93, 0
	v_add_u32_e32 v155, s11, v53
	v_add_u32_e32 v156, s12, v53
	v_lshlrev_b32_e32 v53, 2, v40
	v_lshl_add_u32 v46, v42, 1, 0
	v_lshl_add_u32 v42, v43, 1, 0
	v_lshl_add_u32 v152, v126, 2, s11
	v_mul_lo_u32 v43, v126, s71
	v_add_u32_e32 v153, s11, v52
	v_add_u32_e32 v154, s12, v52
	v_lshl_add_u64 v[130:131], s[0:1], 0, v[48:49]
	v_add_u32_e32 v157, s11, v53
	v_add_u32_e32 v158, s12, v53
	s_add_i32 s66, 0, 0x1a000
	s_add_i32 s0, 0, 0x15800
	v_readlane_b32 s10, v244, 45
	v_cmp_gt_u32_e64 s[12:13], 16, v44
	v_add_u32_e32 v43, 0, v43
	v_and_b32_e32 v47, 48, v40
	s_movk_i32 s1, 0x90
	v_readlane_b32 s11, v244, 46
	s_add_u32 s10, s10, s94
	v_writelane_b32 v244, s12, 63
	v_lshlrev_b32_e32 v50, 2, v45
	v_add_u32_e32 v160, s66, v53
	v_add_u32_e32 v53, s0, v47
	v_mul_lo_u32 v55, v126, s1
	s_addc_u32 s11, s11, 0
	v_writelane_b32 v243, s13, 0
	s_and_b32 s12, s70, 48
	v_lshl_add_u32 v44, v150, 1, s0
	v_mul_lo_u32 v56, v112, s1
	v_mul_lo_u32 v57, v114, s1
	v_mad_u64_u32 v[132:133], s[0:1], v116, s71, v[42:43]
	v_mad_u64_u32 v[134:135], s[0:1], v118, s71, v[42:43]
	v_mad_u64_u32 v[136:137], s[0:1], v120, s71, v[42:43]
	v_mad_u64_u32 v[138:139], s[0:1], v122, s71, v[42:43]
	s_lshl_b32 s13, s12, 1
	v_cmp_gt_i32_e64 s[0:1], v50, v126
	v_or_b32_e32 v59, 33, v50
	v_or_b32_e32 v60, 0x41, v50
	v_and_b32_e32 v41, 24, v41
	s_add_i32 s13, s13, 0
	v_writelane_b32 v243, s0, 1
	v_or_b32_e32 v58, 2, v50
	v_cmp_gt_i32_e64 s[26:27], v59, v126
	v_or_b32_e32 v59, 34, v50
	v_cmp_gt_i32_e64 s[44:45], v60, v126
	v_or_b32_e32 v60, 0x42, v50
	v_add_u32_e32 v54, 0, v41
	v_add_u32_e32 v41, s13, v41
	v_or_b32_e32 v159, s12, v50
	v_writelane_b32 v243, s1, 2
	v_cmp_lt_i32_e64 s[0:1], v50, v126
	v_cmp_gt_i32_e64 s[12:13], v58, v126
	v_or_b32_e32 v58, 3, v50
	v_cmp_gt_i32_e64 s[28:29], v59, v126
	v_or_b32_e32 v59, 35, v50
	v_cmp_gt_i32_e64 s[46:47], v60, v126
	v_or_b32_e32 v60, 0x43, v50
	v_writelane_b32 v243, s0, 3
	v_cmp_gt_i32_e64 s[14:15], v58, v126
	v_or_b32_e32 v58, 16, v50
	v_cmp_gt_i32_e64 s[30:31], v59, v126
	v_or_b32_e32 v59, 48, v50
	v_cmp_gt_i32_e64 s[48:49], v60, v126
	v_or_b32_e32 v60, 0x50, v50
	v_or_b32_e32 v61, 0x61, v50
	v_writelane_b32 v243, s1, 4
	v_cmp_gt_i32_e64 s[0:1], v58, v126
	v_or_b32_e32 v58, 17, v50
	v_cmp_gt_i32_e64 s[34:35], v59, v126
	v_or_b32_e32 v59, 49, v50
	v_cmp_gt_i32_e64 s[50:51], v60, v126
	v_or_b32_e32 v60, 0x51, v50
	v_cmp_gt_i32_e64 s[60:61], v61, v126
	v_or_b32_e32 v61, 0x62, v50
	v_cmp_gt_i32_e64 s[84:85], v58, v126
	v_or_b32_e32 v58, 18, v50
	v_cmp_gt_i32_e64 s[36:37], v59, v126
	v_or_b32_e32 v59, 50, v50
	v_cmp_gt_i32_e64 s[52:53], v60, v126
	v_or_b32_e32 v60, 0x52, v50
	v_cmp_gt_i32_e64 s[62:63], v61, v126
	v_or_b32_e32 v61, 0x63, v50
	v_cmp_gt_i32_e64 s[86:87], v58, v126
	v_or_b32_e32 v58, 19, v50
	v_cmp_gt_i32_e64 s[38:39], v59, v126
	v_or_b32_e32 v59, 51, v50
	v_cmp_gt_i32_e64 s[54:55], v60, v126
	v_or_b32_e32 v60, 0x53, v50
	v_cmp_gt_i32_e64 s[64:65], v61, v126
	v_or_b32_e32 v61, 0x70, v50
	v_lshl_add_u32 v133, v45, 5, s66
	v_or_b32_e32 v45, 32, v48
	v_or_b32_e32 v62, 64, v48
	v_or_b32_e32 v63, 0x60, v48
	v_bfe_u32 v40, v40, 2, 2
	v_cmp_gt_i32_e64 s[88:89], v58, v126
	v_or_b32_e32 v58, 32, v50
	v_cmp_gt_i32_e64 s[40:41], v59, v126
	v_or_b32_e32 v59, 64, v50
	v_cmp_gt_i32_e64 s[56:57], v60, v126
	v_or_b32_e32 v60, 0x60, v50
	v_lshl_add_u32 v135, v45, 2, s66
	v_lshl_add_u32 v137, v62, 2, s66
	v_lshl_add_u32 v139, v63, 2, s66
	v_cmp_gt_i32_e64 s[66:67], v61, v126
	v_or_b32_e32 v61, 0x71, v50
	v_add_u32_e32 v52, 0, v48
	v_cmp_gt_i32_e64 s[24:25], v58, v126
	v_cmp_gt_i32_e64 s[42:43], v59, v126
	v_lshl_add_u64 v[142:143], s[10:11], 0, v[48:49]
	v_cmp_gt_i32_e64 s[68:69], v61, v126
	v_or_b32_e32 v61, 0x72, v50
	v_or_b32_e32 v64, 0x73, v50
	v_or_b32_e32 v49, v50, v40
	v_or_b32_e32 v50, v58, v40
	v_or_b32_e32 v58, v59, v40
	v_or_b32_e32 v59, v60, v40
	v_or_b32_e32 v48, v48, v40
	v_or_b32_e32 v45, v45, v40
	v_or_b32_e32 v62, v62, v40
	v_or_b32_e32 v40, v63, v40
	v_cmp_gt_i32_e64 s[58:59], v60, v126
	v_mul_u32_u24_e32 v60, 0x90, v48
	v_mad_u32_u24 v48, v48, s71, v54
	v_mad_u32_u24 v66, v45, s71, v54
	v_mad_u32_u24 v67, v62, s71, v54
	v_mad_u32_u24 v63, v40, s71, v54
	s_lshl_b32 s10, s3, 5
	s_and_b32 s72, s3, -4
	v_add_u32_e32 v65, 0x440, v48
	s_or_b32 s10, s10, 0x60
	v_add_u32_e32 v68, 0x440, v66
	v_add_u32_e32 v69, 0x440, v67
	v_add_u32_e32 v70, 0x440, v63
	v_add_u32_e32 v161, s10, v48
	v_add_u32_e32 v162, s10, v65
	v_add_u32_e32 v163, s10, v66
; #define LAS __attribute__((address_space(3)))
; __device__ __forceinline__ float bflo(unsigned w) { return __uint_as_float(w << 16); }
; __device__ __forceinline__ float bfhi(unsigned w) { return __uint_as_float(w & 0xffff0000u); }
; __device__ __forceinline__ unsigned pk2(float lo, float hi) { unsigned r; asm("v_cvt_pk_bf16_f32 %0, %1, %2" : "=v"(r) : "v"(lo), "v"(hi)); return r; }
; #define SSD_ISSUE_Z(cn) do { const bf16_t* q_ = PROJ + ((size_t)b * TP + (size_t)(cn) * 128 + trow) * NPROJ + C_Z + h * 64 + 4 * fq; \
;         _Pragma("unroll") for (int pt = 0; pt < 4; ++pt) rz[pt] = *(const u32x2*)(q_ + 16 * pt); } while (0)
; __device__ __forceinline__ void ssd_prompt(const Params& p, LAS unsigned char* lds, int b, int h) {
;     ...
;     const int trow = 16 * wid + fr;
;     u32x4 rx[2], rb[4], rc[4]; u32x2 rz[4]; float rd0 = 0.f, rd1 = 0.f, ra0 = 0.f, ra1 = 0.f;
;     ...
;     SSD_ISSUE(0); SSD_ISSUE_Z(0);
;     for (int c = 0; c < 17; ++c) {
;     ...
;         SSD_ISSUE_Z(cn);
;         __syncthreads();
;         {
;             const float dec = __expf(sAc[127]);
;             const int ptile = wid & 3, nt0 = (wid >> 2) * 4;
; #pragma unroll
;             for (int i = 0; i < 4; ++i) hacc[i] *= dec;
; #pragma unroll
;             for (int kk = 0; kk < 4; ++kk) {
;                 const int sb = 32 * kk + 8 * fq;
;                 const u32x2 xlo = tr4(sX, XROW, sb, 16 * ptile, fr), xhi = tr4(sX, XROW, sb + 4, 16 * ptile, fr);
;                 const f32x4 w0 = *(const LAS f32x4*)(sW + sb), w1 = *(const LAS f32x4*)(sW + sb + 4);
;                 u32x2 blo[4], bhi[4];
; #pragma unroll
;                 for (int i = 0; i < 4; ++i) { blo[i] = tr4(sB, LROW, sb, 16 * (nt0 + i), fr); bhi[i] = tr4(sB, LROW, sb + 4, 16 * (nt0 + i), fr); }
;                 u32x4 w;
;                 w.x = pk2(bflo(xlo.x) * w0[0], bfhi(xlo.x) * w0[1]); w.y = pk2(bflo(xlo.y) * w0[2], bfhi(xlo.y) * w0[3]);
;                 w.z = pk2(bflo(xhi.x) * w1[0], bfhi(xhi.x) * w1[1]); w.w = pk2(bflo(xhi.y) * w1[2], bfhi(xhi.y) * w1[3]);
;                 const bf16x8 xa = __builtin_bit_cast(bf16x8, w);
; #pragma unroll
;                 for (int i = 0; i < 4; ++i) { u32x4 bw; bw.x = blo[i].x; bw.y = blo[i].y; bw.z = bhi[i].x; bw.w = bhi[i].y;
;                     hacc[i] = __builtin_amdgcn_mfma_f32_16x16x32_bf16(xa, __builtin_bit_cast(bf16x8, bw), hacc[i], 0, 0, 0); }
	v_add_u32_e32 v164, s10, v68
	v_add_u32_e32 v165, s10, v67
	v_add_u32_e32 v166, s10, v69
	v_add_u32_e32 v167, s10, v63
	v_add_u32_e32 v168, s10, v70
	s_lshl_b32 s10, s72, 5
	v_add_u32_e32 v169, s10, v48
	v_add_u32_e32 v170, s10, v65
	v_add_u32_e32 v171, s10, v66
	v_add_u32_e32 v172, s10, v68
	v_add_u32_e32 v173, s10, v67
	v_add_u32_e32 v174, s10, v69
	v_add_u32_e32 v175, s10, v63
	v_add_u32_e32 v176, s10, v70
	v_add_u32_e32 v48, s10, v44
	s_lshl_b32 s10, s72, 4
	s_or_b32 s96, s72, 1
	s_or_b32 s91, s72, 2
	s_or_b32 s3, s3, 3
	v_add_u32_e32 v51, 0, v47
	v_mul_u32_u24_e32 v42, 0x110, v150
	v_mul_u32_u24_e32 v49, 0x90, v49
	v_mul_u32_u24_e32 v50, 0x90, v50
	v_mul_u32_u24_e32 v58, 0x90, v58
	v_mul_u32_u24_e32 v59, 0x90, v59
	v_writelane_b32 v243, s10, 5
	v_mul_u32_u24_e32 v45, 0x90, v45
	v_mul_u32_u24_e32 v62, 0x90, v62
	v_mul_u32_u24_e32 v40, 0x90, v40
	v_mul_u32_u24_e32 v63, 0x110, v159
	s_add_i32 s10, s6, s70
	v_lshl_add_u32 v65, s96, 5, v44
	v_lshl_add_u32 v66, s91, 5, v44
	v_lshl_add_u32 v44, s3, 5, v44
	v_or_b32_e32 v177, s10, v150
	s_mov_b32 s23, s3
	v_add_u32_e32 v178, v46, v56
	v_add_u32_e32 v179, v46, v57
	s_lshl_b32 s94, s2, 1
	s_add_i32 s97, 0, 0x19ffc
	v_add_u32_e32 v180, v43, v47
	v_add_u32_e32 v181, v51, v42
	v_add_u32_e32 v182, v53, v42
	v_add_u32_e32 v183, v54, v49
	v_add_u32_e32 v185, v54, v50
	v_add_u32_e32 v186, v54, v58
	v_add_u32_e32 v187, v54, v59
	v_add_u32_e32 v188, v52, v55
	v_mbcnt_hi_u32_b32 v189, -1, v184
	v_add_u32_e32 v190, v41, v60
	v_add_u32_e32 v191, v41, v45
	v_add_u32_e32 v193, v41, v62
	v_add_u32_e32 v194, v41, v40
	v_add_u32_e32 v195, v48, v63
	v_add_u32_e32 v196, v65, v63
	v_add_u32_e32 v197, v66, v63
	v_add_u32_e32 v198, v44, v63
	v_mov_b32_e32 v48, v109
	v_mov_b32_e32 v49, v109
	v_mov_b32_e32 v50, v109
	v_mov_b32_e32 v51, v109
	v_mov_b32_e32 v52, v109
	v_mov_b32_e32 v53, v109
	v_mov_b32_e32 v54, v109
	v_mov_b32_e32 v55, v109
	v_mov_b32_e32 v44, v109
	v_mov_b32_e32 v45, v109
	v_mov_b32_e32 v46, v109
	v_mov_b32_e32 v47, v109
	v_mov_b32_e32 v40, v109
	v_mov_b32_e32 v41, v109
	v_mov_b32_e32 v42, v109
	v_mov_b32_e32 v43, v109
	s_mov_b32 s2, s95
	v_cmp_gt_i32_e64 s[70:71], v61, v126
	v_cmp_gt_i32_e64 s[72:73], v64, v126
	v_readfirstlane_b32 s98, v192
	s_nop 0
	s_cmp_lt_u32 s98, 0x100
	s_cbranch_scc1 .Lp2prio_skip
	s_setprio 1
.Lp2prio_skip:
	s_branch .LBB0_530
.LBB0_529:
	s_or_b64 exec, exec, s[2:3]
	s_waitcnt lgkmcnt(0)
	v_lshl_add_u64 v[56:57], s[10:11], 0, v[126:127]
	v_mad_u64_u32 v[58:59], s[2:3], v56, s83, v[130:131]
	v_mov_b32_e32 v56, v59
	v_mad_u64_u32 v[56:57], s[2:3], v57, s83, v[56:57]
	v_mov_b32_e32 v59, v56
	v_mov_b32_e32 v56, s97
	global_load_dwordx2 v[148:149], v[58:59], off
	global_load_dwordx2 v[146:147], v[58:59], off offset:32
	global_load_dwordx2 v[144:145], v[58:59], off offset:64
	global_load_dwordx2 v[140:141], v[58:59], off offset:96
	s_barrier
	ds_read_b32 v56, v56
	ds_read_b64_tr_b16 v[74:75], v190
	ds_read_b64_tr_b16 v[76:77], v190 offset:576
	s_cmpk_lg_i32 s90, 0x880
	s_mov_b32 s2, s90
	s_waitcnt lgkmcnt(2)
	v_mul_f32_e32 v56, 0x3fb8aa3b, v56
	v_exp_f32_e32 v72, v56
	ds_read_b128 v[56:59], v133
	ds_read_b128 v[60:63], v133 offset:16
	ds_read_b64_tr_b16 v[66:67], v170 offset:18464
	ds_read_b64_tr_b16 v[68:69], v169 offset:18432
	ds_read_b64_tr_b16 v[64:65], v169 offset:18464
	ds_read_b64_tr_b16 v[70:71], v170 offset:18432
	v_mul_f32_e32 v50, v50, v72
	v_mul_f32_e32 v51, v51, v72
	v_mul_f32_e32 v48, v48, v72
	v_mul_f32_e32 v49, v49, v72
	v_mul_f32_e32 v54, v54, v72
	v_mul_f32_e32 v55, v55, v72
	v_mul_f32_e32 v52, v52, v72
	v_mul_f32_e32 v53, v53, v72
	s_waitcnt lgkmcnt(7)
	v_lshlrev_b32_e32 v73, 16, v74
	s_waitcnt lgkmcnt(5)
	v_mul_f32_e32 v56, v56, v73
	v_and_b32_e32 v73, 0xffff0000, v74
	v_mul_f32_e32 v57, v57, v73
	v_cvt_pk_bf16_f32 v56, v56, v57
	v_lshlrev_b32_e32 v57, 16, v75
	v_mul_f32_e32 v57, v58, v57
	v_and_b32_e32 v58, 0xffff0000, v75
	v_mul_f32_e32 v58, v59, v58
	v_cvt_pk_bf16_f32 v57, v57, v58
	v_lshlrev_b32_e32 v58, 16, v76
	v_and_b32_e32 v59, 0xffff0000, v76
	s_waitcnt lgkmcnt(4)
	v_mul_f32_e32 v58, v60, v58
	v_mul_f32_e32 v59, v61, v59
	v_cvt_pk_bf16_f32 v58, v58, v59
	v_lshlrev_b32_e32 v59, 16, v77
	v_and_b32_e32 v60, 0xffff0000, v77
	v_mul_f32_e32 v59, v62, v59
	v_mul_f32_e32 v60, v63, v60
	v_cvt_pk_bf16_f32 v59, v59, v60
	v_mul_f32_e32 v46, v46, v72
	v_mul_f32_e32 v47, v47, v72
	s_waitcnt lgkmcnt(0)
	v_mfma_f32_16x16x32_bf16 v[48:51], v[56:59], v[68:71], v[48:51]
	ds_read_b64_tr_b16 v[60:61], v169 offset:18496
	ds_read_b64_tr_b16 v[62:63], v170 offset:18496
	ds_read_b64_tr_b16 v[68:69], v161 offset:18432
	ds_read_b64_tr_b16 v[70:71], v162 offset:18432
	ds_read_b64_tr_b16 v[74:75], v191
	v_mul_f32_e32 v44, v44, v72
	v_mul_f32_e32 v45, v45, v72
	v_mul_f32_e32 v42, v42, v72
	v_mul_f32_e32 v43, v43, v72
	v_mul_f32_e32 v40, v40, v72
	v_mul_f32_e32 v41, v41, v72
	v_mfma_f32_16x16x32_bf16 v[52:55], v[56:59], v[64:67], v[52:55]
	s_waitcnt lgkmcnt(0)
	v_lshlrev_b32_e32 v72, 16, v74
	v_mfma_f32_16x16x32_bf16 v[44:47], v[56:59], v[60:63], v[44:47]
	v_mfma_f32_16x16x32_bf16 v[40:43], v[56:59], v[68:71], v[40:43]
	ds_read_b64_tr_b16 v[70:71], v191 offset:576
	ds_read_b128 v[56:59], v135
	ds_read_b128 v[60:63], v135 offset:16
	ds_read_b64_tr_b16 v[64:65], v172 offset:18464
	ds_read_b64_tr_b16 v[66:67], v171 offset:18432
	ds_read_b64_tr_b16 v[68:69], v172 offset:18432
	s_waitcnt lgkmcnt(4)
; #define LAS __attribute__((address_space(3)))
; __device__ __forceinline__ float bflo(unsigned w) { return __uint_as_float(w << 16); }
; __device__ __forceinline__ float bfhi(unsigned w) { return __uint_as_float(w & 0xffff0000u); }
; __device__ __forceinline__ unsigned pk2(float lo, float hi) { unsigned r; asm("v_cvt_pk_bf16_f32 %0, %1, %2" : "=v"(r) : "v"(lo), "v"(hi)); return r; }
; __device__ __forceinline__ bf16_t f2bf(float f) { return (bf16_t)(pk2(f, 0.f) & 0xffffu); }
; __device__ __forceinline__ void ssd_prompt(const Params& p, LAS unsigned char* lds, int b, int h) {
;     ...
;             for (int kk = 0; kk < 4; ++kk) {
;                 const int sb = 32 * kk + 8 * fq;
;                 const u32x2 xlo = tr4(sX, XROW, sb, 16 * ptile, fr), xhi = tr4(sX, XROW, sb + 4, 16 * ptile, fr);
;                 const f32x4 w0 = *(const LAS f32x4*)(sW + sb), w1 = *(const LAS f32x4*)(sW + sb + 4);
;                 u32x2 blo[4], bhi[4];
; #pragma unroll
;                 for (int i = 0; i < 4; ++i) { blo[i] = tr4(sB, LROW, sb, 16 * (nt0 + i), fr); bhi[i] = tr4(sB, LROW, sb + 4, 16 * (nt0 + i), fr); }
;                 u32x4 w;
;                 w.x = pk2(bflo(xlo.x) * w0[0], bfhi(xlo.x) * w0[1]); w.y = pk2(bflo(xlo.y) * w0[2], bfhi(xlo.y) * w0[3]);
;                 w.z = pk2(bflo(xhi.x) * w1[0], bfhi(xhi.x) * w1[1]); w.w = pk2(bflo(xhi.y) * w1[2], bfhi(xhi.y) * w1[3]);
;                 const bf16x8 xa = __builtin_bit_cast(bf16x8, w);
; #pragma unroll
;                 for (int i = 0; i < 4; ++i) { u32x4 bw; bw.x = blo[i].x; bw.y = blo[i].y; bw.z = bhi[i].x; bw.w = bhi[i].y;
;                     hacc[i] = __builtin_amdgcn_mfma_f32_16x16x32_bf16(xa, __builtin_bit_cast(bf16x8, bw), hacc[i], 0, 0, 0); }
;             }
; #pragma unroll
;             for (int i = 0; i < 4; ++i)
; #pragma unroll
;                 for (int jj = 0; jj < 4; ++jj) sH[(16 * ptile + 4 * fq + jj) * LROW + 16 * (nt0 + i) + fr] = f2bf(hacc[i][jj]);
;         }
;         __syncthreads();
	v_mul_f32_e32 v56, v56, v72
	v_and_b32_e32 v72, 0xffff0000, v74
	v_mul_f32_e32 v57, v57, v72
	v_cvt_pk_bf16_f32 v56, v56, v57
	v_lshlrev_b32_e32 v57, 16, v75
	v_mul_f32_e32 v57, v58, v57
	v_and_b32_e32 v58, 0xffff0000, v75
	v_mul_f32_e32 v58, v59, v58
	v_cvt_pk_bf16_f32 v57, v57, v58
	v_lshlrev_b32_e32 v58, 16, v70
	v_and_b32_e32 v59, 0xffff0000, v70
	s_waitcnt lgkmcnt(3)
	v_mul_f32_e32 v58, v60, v58
	v_mul_f32_e32 v59, v61, v59
	v_cvt_pk_bf16_f32 v58, v58, v59
	v_lshlrev_b32_e32 v59, 16, v71
	v_and_b32_e32 v60, 0xffff0000, v71
	v_mul_f32_e32 v59, v62, v59
	v_mul_f32_e32 v60, v63, v60
	v_cvt_pk_bf16_f32 v59, v59, v60
	ds_read_b64_tr_b16 v[62:63], v171 offset:18464
	ds_read_b64_tr_b16 v[60:61], v171 offset:18496
	s_waitcnt lgkmcnt(1)
	v_mfma_f32_16x16x32_bf16 v[52:55], v[56:59], v[62:65], v[52:55]
	ds_read_b64_tr_b16 v[62:63], v172 offset:18496
	ds_read_b64_tr_b16 v[64:65], v163 offset:18432
	v_mfma_f32_16x16x32_bf16 v[48:51], v[56:59], v[66:69], v[48:51]
	ds_read_b64_tr_b16 v[66:67], v164 offset:18432
	ds_read_b64_tr_b16 v[70:71], v193
	ds_read_b64_tr_b16 v[72:73], v193 offset:576
	s_waitcnt lgkmcnt(1)
	v_lshlrev_b32_e32 v74, 16, v70
	v_mfma_f32_16x16x32_bf16 v[44:47], v[56:59], v[60:63], v[44:47]
	v_and_b32_e32 v70, 0xffff0000, v70
	v_mfma_f32_16x16x32_bf16 v[40:43], v[56:59], v[64:67], v[40:43]
	ds_read_b128 v[56:59], v137
	ds_read_b128 v[60:63], v137 offset:16
	ds_read_b64_tr_b16 v[64:65], v174 offset:18464
	ds_read_b64_tr_b16 v[66:67], v173 offset:18432
	ds_read_b64_tr_b16 v[68:69], v174 offset:18432
	s_waitcnt lgkmcnt(4)
	v_mul_f32_e32 v56, v56, v74
	v_mul_f32_e32 v57, v57, v70
	v_cvt_pk_bf16_f32 v56, v56, v57
	v_lshlrev_b32_e32 v57, 16, v71
	v_mul_f32_e32 v57, v58, v57
	v_and_b32_e32 v58, 0xffff0000, v71
	v_mul_f32_e32 v58, v59, v58
	v_cvt_pk_bf16_f32 v57, v57, v58
	v_lshlrev_b32_e32 v58, 16, v72
	v_and_b32_e32 v59, 0xffff0000, v72
	s_waitcnt lgkmcnt(3)
	v_mul_f32_e32 v58, v60, v58
	v_mul_f32_e32 v59, v61, v59
	v_cvt_pk_bf16_f32 v58, v58, v59
	v_lshlrev_b32_e32 v59, 16, v73
	v_and_b32_e32 v60, 0xffff0000, v73
	v_mul_f32_e32 v59, v62, v59
	v_mul_f32_e32 v60, v63, v60
	v_cvt_pk_bf16_f32 v59, v59, v60
	ds_read_b64_tr_b16 v[62:63], v173 offset:18464
	ds_read_b64_tr_b16 v[60:61], v173 offset:18496
	s_waitcnt lgkmcnt(2)
	v_mfma_f32_16x16x32_bf16 v[48:51], v[56:59], v[66:69], v[48:51]
	s_waitcnt lgkmcnt(1)
	v_mfma_f32_16x16x32_bf16 v[52:55], v[56:59], v[62:65], v[52:55]
	ds_read_b64_tr_b16 v[62:63], v174 offset:18496
	ds_read_b64_tr_b16 v[64:65], v165 offset:18432
	ds_read_b64_tr_b16 v[66:67], v166 offset:18432
	ds_read_b64_tr_b16 v[70:71], v194
	s_waitcnt lgkmcnt(0)
	v_lshlrev_b32_e32 v74, 16, v70
	v_mfma_f32_16x16x32_bf16 v[44:47], v[56:59], v[60:63], v[44:47]
	v_and_b32_e32 v70, 0xffff0000, v70
	v_mfma_f32_16x16x32_bf16 v[40:43], v[56:59], v[64:67], v[40:43]
	ds_read_b64_tr_b16 v[72:73], v194 offset:576
	ds_read_b128 v[56:59], v139
	ds_read_b128 v[60:63], v139 offset:16
	ds_read_b64_tr_b16 v[64:65], v176 offset:18464
	ds_read_b64_tr_b16 v[66:67], v175 offset:18432
	ds_read_b64_tr_b16 v[68:69], v176 offset:18432
	s_waitcnt lgkmcnt(4)
	v_mul_f32_e32 v56, v56, v74
	v_mul_f32_e32 v57, v57, v70
	v_cvt_pk_bf16_f32 v56, v56, v57
	v_lshlrev_b32_e32 v57, 16, v71
	v_mul_f32_e32 v57, v58, v57
	v_and_b32_e32 v58, 0xffff0000, v71
	v_mul_f32_e32 v58, v59, v58
	v_cvt_pk_bf16_f32 v57, v57, v58
	v_lshlrev_b32_e32 v58, 16, v72
	v_and_b32_e32 v59, 0xffff0000, v72
	s_waitcnt lgkmcnt(3)
	v_mul_f32_e32 v58, v60, v58
	v_mul_f32_e32 v59, v61, v59
	v_cvt_pk_bf16_f32 v58, v58, v59
	v_lshlrev_b32_e32 v59, 16, v73
	v_and_b32_e32 v60, 0xffff0000, v73
	v_mul_f32_e32 v59, v62, v59
	v_mul_f32_e32 v60, v63, v60
	v_cvt_pk_bf16_f32 v59, v59, v60
	ds_read_b64_tr_b16 v[62:63], v175 offset:18464
	ds_read_b64_tr_b16 v[60:61], v175 offset:18496
	s_waitcnt lgkmcnt(2)
	v_mfma_f32_16x16x32_bf16 v[48:51], v[56:59], v[66:69], v[48:51]
	s_waitcnt lgkmcnt(1)
	v_mfma_f32_16x16x32_bf16 v[52:55], v[56:59], v[62:65], v[52:55]
	ds_read_b64_tr_b16 v[62:63], v176 offset:18496
	ds_read_b64_tr_b16 v[64:65], v167 offset:18432
	ds_read_b64_tr_b16 v[66:67], v168 offset:18432
	s_waitcnt lgkmcnt(2)
	v_mfma_f32_16x16x32_bf16 v[44:47], v[56:59], v[60:63], v[44:47]
	s_waitcnt lgkmcnt(0)
	v_mfma_f32_16x16x32_bf16 v[40:43], v[56:59], v[64:67], v[40:43]
	v_cvt_pk_bf16_f32 v56, v48, v109
	ds_write_b16 v195, v56
	v_cvt_pk_bf16_f32 v56, v49, v109
	ds_write_b16 v195, v56 offset:272
	v_cvt_pk_bf16_f32 v56, v50, v109
	ds_write_b16 v195, v56 offset:544
	v_cvt_pk_bf16_f32 v56, v51, v109
	ds_write_b16 v195, v56 offset:816
	v_cvt_pk_bf16_f32 v56, v52, v109
	ds_write_b16 v196, v56
	v_cvt_pk_bf16_f32 v56, v53, v109
	ds_write_b16 v196, v56 offset:272
	v_cvt_pk_bf16_f32 v56, v54, v109
	ds_write_b16 v196, v56 offset:544
	v_cvt_pk_bf16_f32 v56, v55, v109
	ds_write_b16 v196, v56 offset:816
	v_cvt_pk_bf16_f32 v56, v44, v109
	ds_write_b16 v197, v56
	v_cvt_pk_bf16_f32 v56, v45, v109
	ds_write_b16 v197, v56 offset:272
	v_cvt_pk_bf16_f32 v56, v46, v109
	ds_write_b16 v197, v56 offset:544
	v_cvt_pk_bf16_f32 v56, v47, v109
	ds_write_b16 v197, v56 offset:816
	v_cvt_pk_bf16_f32 v56, v40, v109
	ds_write_b16 v198, v56
	v_cvt_pk_bf16_f32 v56, v41, v109
	ds_write_b16 v198, v56 offset:272
	v_cvt_pk_bf16_f32 v56, v42, v109
	ds_write_b16 v198, v56 offset:544
	v_cvt_pk_bf16_f32 v56, v43, v109
	ds_write_b16 v198, v56 offset:816
	s_waitcnt lgkmcnt(0)
	s_barrier
	s_cbranch_scc0 .LBB0_538

; __device__ __forceinline__ void ssd_prompt(const Params& p, LAS unsigned char* lds, int b, int h) {
;     ...
;     { const int ptile = wid & 3, nt0 = (wid >> 2) * 4; float* dst = p.out + O_SP + ((size_t)(b * 32 + h) * 64) * 128;
; #pragma unroll
;         for (int i = 0; i < 4; ++i)
; #pragma unroll
;             for (int jj = 0; jj < 4; ++jj) dst[(16 * ptile + 4 * fq + jj) * 128 + 16 * (nt0 + i) + fr] = hacc[i][jj]; }
.LBB0_538:
	s_setprio 0
	s_lshl_b32 s0, s80, 5
	s_or_b32 s0, s33, s0
	s_ashr_i32 s1, s0, 31
	v_readlane_b32 s4, v244, 47
	s_lshl_b64 s[0:1], s[0:1], 15
	v_readlane_b32 s6, v244, 49
	v_readlane_b32 s7, v244, 50
	s_add_u32 s0, s6, s0
	v_readlane_b32 s2, v243, 5
	s_addc_u32 s1, s7, s1
	s_waitcnt vmcnt(17)
	v_lshlrev_b32_e32 v2, 7, v159
	v_or_b32_e32 v0, s2, v150
	s_add_u32 s0, s0, 0x4824000
	v_add_u32_e32 v0, v2, v0
	s_addc_u32 s1, s1, 0
	v_ashrrev_i32_e32 v1, 31, v0
	v_lshl_add_u64 v[0:1], v[0:1], 2, s[0:1]
	global_store_dword v[0:1], v48, off
	global_store_dword v[0:1], v49, off offset:512
	global_store_dword v[0:1], v50, off offset:1024
	global_store_dword v[0:1], v51, off offset:1536
	v_lshl_or_b32 v0, s96, 4, v150
	v_add_u32_e32 v0, v2, v0
	v_ashrrev_i32_e32 v1, 31, v0
	v_lshl_add_u64 v[0:1], v[0:1], 2, s[0:1]
	global_store_dword v[0:1], v52, off
	global_store_dword v[0:1], v53, off offset:512
	global_store_dword v[0:1], v54, off offset:1024
	global_store_dword v[0:1], v55, off offset:1536
	v_lshl_or_b32 v0, s91, 4, v150
	v_add_u32_e32 v0, v2, v0
	v_ashrrev_i32_e32 v1, 31, v0
	v_lshl_add_u64 v[0:1], v[0:1], 2, s[0:1]
	global_store_dword v[0:1], v44, off
	global_store_dword v[0:1], v45, off offset:512
	global_store_dword v[0:1], v46, off offset:1024
	global_store_dword v[0:1], v47, off offset:1536
	v_lshl_or_b32 v0, s23, 4, v150
	v_readlane_b32 s10, v244, 53
	v_readlane_b32 s11, v244, 54
	v_add_u32_e32 v0, v2, v0
	v_readlane_b32 s5, v244, 48
	v_readlane_b32 s8, v244, 51
	v_readlane_b32 s9, v244, 52
	s_mov_b64 s[90:91], s[10:11]
	v_ashrrev_i32_e32 v1, 31, v0
	v_readlane_b32 s96, v244, 55
	s_mov_b64 s[88:89], s[8:9]
	s_mov_b64 s[86:87], s[6:7]
	s_mov_b64 s[84:85], s[4:5]
	v_lshl_add_u64 v[0:1], v[0:1], 2, s[0:1]
	v_readlane_b32 s83, v244, 59
	v_readlane_b32 s94, v244, 57
	v_readlane_b32 s97, v244, 56
	global_store_dword v[0:1], v40, off
	global_store_dword v[0:1], v41, off offset:512
	global_store_dword v[0:1], v42, off offset:1024
	global_store_dword v[0:1], v43, off offset:1536
